# fast bf16 store epilogue for nsa_q tiles with only query columns (tn<8); gate tiles keep compiled path
# speedup vs baseline: 1.0065x; 1.0042x over previous
.LBB0_344:
	s_cmp_lt_u32 s4, 8
	s_cbranch_scc0 .Lnqa_slow
	v_lshrrev_b32_e32 v66, 1, v206
	v_and_b32_e32 v66, 0xffffffc0, v66
	v_lshrrev_b32_e32 v67, 3, v206
	v_and_or_b32 v66, v67, 4, v66
	v_lshl_add_u32 v68, s2, 7, v66
	v_lshrrev_b32_e32 v67, 1, v206
	v_and_b32_e32 v67, 32, v67
	v_and_b32_e32 v69, 31, v206
	s_lshl_b32 s6, s4, 7
	v_or3_b32 v66, v69, v67, s6
	v_readlane_b32 s14, v248, 2
	v_readlane_b32 s15, v248, 3
	v_mov_b32_e32 v69, 0
	v_mov_b32_e32 v67, 0
	v_lshlrev_b64 v[70:71], 11, v[68:69]
	v_lshlrev_b32_e32 v66, 1, v66
	v_lshl_add_u64 v[70:71], s[14:15], 0, v[70:71]
	v_lshl_add_u64 v[70:71], v[66:67], 0, v[70:71]
	s_movk_i32 s7, 0x7fff
	v_mul_f32_e32 v50, 0x3e38aa3b, v50
	v_bfe_u32 v74, v50, 16, 1
	v_add3_u32 v50, v50, v74, s7
	global_store_short_d16_hi v[70:71], v50, off
	v_mul_f32_e32 v34, 0x3e38aa3b, v34
	v_bfe_u32 v74, v34, 16, 1
	v_add3_u32 v34, v34, v74, s7
	global_store_short_d16_hi v[70:71], v34, off offset:128
	v_mul_f32_e32 v51, 0x3e38aa3b, v51
	v_bfe_u32 v74, v51, 16, 1
	v_add3_u32 v51, v51, v74, s7
	global_store_short_d16_hi v[70:71], v51, off offset:2048
	v_mul_f32_e32 v35, 0x3e38aa3b, v35
	v_bfe_u32 v74, v35, 16, 1
	v_add3_u32 v35, v35, v74, s7
	global_store_short_d16_hi v[70:71], v35, off offset:2176
	s_mov_b32 s6, 0x1000
	v_add_co_u32_e32 v72, vcc, s6, v70
	s_nop 1
	v_addc_co_u32_e32 v73, vcc, 0, v71, vcc
	v_mul_f32_e32 v52, 0x3e38aa3b, v52
	v_bfe_u32 v74, v52, 16, 1
	v_add3_u32 v52, v52, v74, s7
	global_store_short_d16_hi v[72:73], v52, off
	v_mul_f32_e32 v36, 0x3e38aa3b, v36
	v_bfe_u32 v74, v36, 16, 1
	v_add3_u32 v36, v36, v74, s7
	global_store_short_d16_hi v[72:73], v36, off offset:128
	v_mul_f32_e32 v53, 0x3e38aa3b, v53
	v_bfe_u32 v74, v53, 16, 1
	v_add3_u32 v53, v53, v74, s7
	global_store_short_d16_hi v[72:73], v53, off offset:2048
	v_mul_f32_e32 v37, 0x3e38aa3b, v37
	v_bfe_u32 v74, v37, 16, 1
	v_add3_u32 v37, v37, v74, s7
	global_store_short_d16_hi v[72:73], v37, off offset:2176
	s_mov_b32 s6, 0x4000
	v_add_co_u32_e32 v72, vcc, s6, v70
	s_nop 1
	v_addc_co_u32_e32 v73, vcc, 0, v71, vcc
	v_mul_f32_e32 v54, 0x3e38aa3b, v54
	v_bfe_u32 v74, v54, 16, 1
	v_add3_u32 v54, v54, v74, s7
	global_store_short_d16_hi v[72:73], v54, off
	v_mul_f32_e32 v38, 0x3e38aa3b, v38
	v_bfe_u32 v74, v38, 16, 1
	v_add3_u32 v38, v38, v74, s7
	global_store_short_d16_hi v[72:73], v38, off offset:128
	v_mul_f32_e32 v55, 0x3e38aa3b, v55
	v_bfe_u32 v74, v55, 16, 1
	v_add3_u32 v55, v55, v74, s7
	global_store_short_d16_hi v[72:73], v55, off offset:2048
	v_mul_f32_e32 v39, 0x3e38aa3b, v39
	v_bfe_u32 v74, v39, 16, 1
	v_add3_u32 v39, v39, v74, s7
	global_store_short_d16_hi v[72:73], v39, off offset:2176
	s_mov_b32 s6, 0x5000
	v_add_co_u32_e32 v72, vcc, s6, v70
	s_nop 1
	v_addc_co_u32_e32 v73, vcc, 0, v71, vcc
	v_mul_f32_e32 v56, 0x3e38aa3b, v56
	v_bfe_u32 v74, v56, 16, 1
	v_add3_u32 v56, v56, v74, s7
	global_store_short_d16_hi v[72:73], v56, off
	v_mul_f32_e32 v40, 0x3e38aa3b, v40
	v_bfe_u32 v74, v40, 16, 1
	v_add3_u32 v40, v40, v74, s7
	global_store_short_d16_hi v[72:73], v40, off offset:128
	v_mul_f32_e32 v57, 0x3e38aa3b, v57
	v_bfe_u32 v74, v57, 16, 1
	v_add3_u32 v57, v57, v74, s7
	global_store_short_d16_hi v[72:73], v57, off offset:2048
	v_mul_f32_e32 v41, 0x3e38aa3b, v41
	v_bfe_u32 v74, v41, 16, 1
	v_add3_u32 v41, v41, v74, s7
	global_store_short_d16_hi v[72:73], v41, off offset:2176
	s_mov_b32 s6, 0x8000
	v_add_co_u32_e32 v72, vcc, s6, v70
	s_nop 1
	v_addc_co_u32_e32 v73, vcc, 0, v71, vcc
	v_mul_f32_e32 v58, 0x3e38aa3b, v58
	v_bfe_u32 v74, v58, 16, 1
	v_add3_u32 v58, v58, v74, s7
	global_store_short_d16_hi v[72:73], v58, off
	v_mul_f32_e32 v42, 0x3e38aa3b, v42
	v_bfe_u32 v74, v42, 16, 1
	v_add3_u32 v42, v42, v74, s7
	global_store_short_d16_hi v[72:73], v42, off offset:128
	v_mul_f32_e32 v59, 0x3e38aa3b, v59
	v_bfe_u32 v74, v59, 16, 1
	v_add3_u32 v59, v59, v74, s7
	global_store_short_d16_hi v[72:73], v59, off offset:2048
	v_mul_f32_e32 v43, 0x3e38aa3b, v43
	v_bfe_u32 v74, v43, 16, 1
	v_add3_u32 v43, v43, v74, s7
	global_store_short_d16_hi v[72:73], v43, off offset:2176
	s_mov_b32 s6, 0x9000
	v_add_co_u32_e32 v72, vcc, s6, v70
	s_nop 1
	v_addc_co_u32_e32 v73, vcc, 0, v71, vcc
	v_mul_f32_e32 v60, 0x3e38aa3b, v60
	v_bfe_u32 v74, v60, 16, 1
	v_add3_u32 v60, v60, v74, s7
	global_store_short_d16_hi v[72:73], v60, off
	v_mul_f32_e32 v44, 0x3e38aa3b, v44
	v_bfe_u32 v74, v44, 16, 1
	v_add3_u32 v44, v44, v74, s7
	global_store_short_d16_hi v[72:73], v44, off offset:128
	v_mul_f32_e32 v61, 0x3e38aa3b, v61
	v_bfe_u32 v74, v61, 16, 1
	v_add3_u32 v61, v61, v74, s7
	global_store_short_d16_hi v[72:73], v61, off offset:2048
	v_mul_f32_e32 v45, 0x3e38aa3b, v45
	v_bfe_u32 v74, v45, 16, 1
	v_add3_u32 v45, v45, v74, s7
	global_store_short_d16_hi v[72:73], v45, off offset:2176
	s_mov_b32 s6, 0xc000
	v_add_co_u32_e32 v72, vcc, s6, v70
	s_nop 1
	v_addc_co_u32_e32 v73, vcc, 0, v71, vcc
	v_mul_f32_e32 v62, 0x3e38aa3b, v62
	v_bfe_u32 v74, v62, 16, 1
	v_add3_u32 v62, v62, v74, s7
	global_store_short_d16_hi v[72:73], v62, off
	v_mul_f32_e32 v46, 0x3e38aa3b, v46
	v_bfe_u32 v74, v46, 16, 1
	v_add3_u32 v46, v46, v74, s7
	global_store_short_d16_hi v[72:73], v46, off offset:128
	v_mul_f32_e32 v63, 0x3e38aa3b, v63
	v_bfe_u32 v74, v63, 16, 1
	v_add3_u32 v63, v63, v74, s7
	global_store_short_d16_hi v[72:73], v63, off offset:2048
	v_mul_f32_e32 v47, 0x3e38aa3b, v47
	v_bfe_u32 v74, v47, 16, 1
	v_add3_u32 v47, v47, v74, s7
	global_store_short_d16_hi v[72:73], v47, off offset:2176
	s_mov_b32 s6, 0xd000
	v_add_co_u32_e32 v72, vcc, s6, v70
	s_nop 1
	v_addc_co_u32_e32 v73, vcc, 0, v71, vcc
	v_mul_f32_e32 v64, 0x3e38aa3b, v64
	v_bfe_u32 v74, v64, 16, 1
	v_add3_u32 v64, v64, v74, s7
	global_store_short_d16_hi v[72:73], v64, off
	v_mul_f32_e32 v48, 0x3e38aa3b, v48
	v_bfe_u32 v74, v48, 16, 1
	v_add3_u32 v48, v48, v74, s7
	global_store_short_d16_hi v[72:73], v48, off offset:128
	v_mul_f32_e32 v65, 0x3e38aa3b, v65
	v_bfe_u32 v74, v65, 16, 1
	v_add3_u32 v65, v65, v74, s7
	global_store_short_d16_hi v[72:73], v65, off offset:2048
	v_mul_f32_e32 v49, 0x3e38aa3b, v49
	v_bfe_u32 v74, v49, 16, 1
	v_add3_u32 v49, v49, v74, s7
	global_store_short_d16_hi v[72:73], v49, off offset:2176
	s_mov_b32 s6, 0x10000
	v_add_co_u32_e32 v72, vcc, s6, v70
	s_nop 1
	v_addc_co_u32_e32 v73, vcc, 0, v71, vcc
	v_mul_f32_e32 v16, 0x3e38aa3b, v16
	v_bfe_u32 v74, v16, 16, 1
	v_add3_u32 v16, v16, v74, s7
	global_store_short_d16_hi v[72:73], v16, off
	v_mul_f32_e32 v0, 0x3e38aa3b, v0
	v_bfe_u32 v74, v0, 16, 1
	v_add3_u32 v0, v0, v74, s7
	global_store_short_d16_hi v[72:73], v0, off offset:128
	v_mul_f32_e32 v17, 0x3e38aa3b, v17
	v_bfe_u32 v74, v17, 16, 1
	v_add3_u32 v17, v17, v74, s7
	global_store_short_d16_hi v[72:73], v17, off offset:2048
	v_mul_f32_e32 v1, 0x3e38aa3b, v1
	v_bfe_u32 v74, v1, 16, 1
	v_add3_u32 v1, v1, v74, s7
	global_store_short_d16_hi v[72:73], v1, off offset:2176
	s_mov_b32 s6, 0x11000
	v_add_co_u32_e32 v72, vcc, s6, v70
	s_nop 1
	v_addc_co_u32_e32 v73, vcc, 0, v71, vcc
	v_mul_f32_e32 v18, 0x3e38aa3b, v18
	v_bfe_u32 v74, v18, 16, 1
	v_add3_u32 v18, v18, v74, s7
	global_store_short_d16_hi v[72:73], v18, off
	v_mul_f32_e32 v2, 0x3e38aa3b, v2
	v_bfe_u32 v74, v2, 16, 1
	v_add3_u32 v2, v2, v74, s7
	global_store_short_d16_hi v[72:73], v2, off offset:128
	v_mul_f32_e32 v19, 0x3e38aa3b, v19
	v_bfe_u32 v74, v19, 16, 1
	v_add3_u32 v19, v19, v74, s7
	global_store_short_d16_hi v[72:73], v19, off offset:2048
	v_mul_f32_e32 v3, 0x3e38aa3b, v3
	v_bfe_u32 v74, v3, 16, 1
	v_add3_u32 v3, v3, v74, s7
	global_store_short_d16_hi v[72:73], v3, off offset:2176
	s_mov_b32 s6, 0x14000
	v_add_co_u32_e32 v72, vcc, s6, v70
	s_nop 1
	v_addc_co_u32_e32 v73, vcc, 0, v71, vcc
	v_mul_f32_e32 v20, 0x3e38aa3b, v20
	v_bfe_u32 v74, v20, 16, 1
	v_add3_u32 v20, v20, v74, s7
	global_store_short_d16_hi v[72:73], v20, off
	v_mul_f32_e32 v4, 0x3e38aa3b, v4
	v_bfe_u32 v74, v4, 16, 1
	v_add3_u32 v4, v4, v74, s7
	global_store_short_d16_hi v[72:73], v4, off offset:128
	v_mul_f32_e32 v21, 0x3e38aa3b, v21
	v_bfe_u32 v74, v21, 16, 1
	v_add3_u32 v21, v21, v74, s7
	global_store_short_d16_hi v[72:73], v21, off offset:2048
	v_mul_f32_e32 v5, 0x3e38aa3b, v5
	v_bfe_u32 v74, v5, 16, 1
	v_add3_u32 v5, v5, v74, s7
	global_store_short_d16_hi v[72:73], v5, off offset:2176
	s_mov_b32 s6, 0x15000
	v_add_co_u32_e32 v72, vcc, s6, v70
	s_nop 1
	v_addc_co_u32_e32 v73, vcc, 0, v71, vcc
	v_mul_f32_e32 v22, 0x3e38aa3b, v22
	v_bfe_u32 v74, v22, 16, 1
	v_add3_u32 v22, v22, v74, s7
	global_store_short_d16_hi v[72:73], v22, off
	v_mul_f32_e32 v6, 0x3e38aa3b, v6
	v_bfe_u32 v74, v6, 16, 1
	v_add3_u32 v6, v6, v74, s7
	global_store_short_d16_hi v[72:73], v6, off offset:128
	v_mul_f32_e32 v23, 0x3e38aa3b, v23
	v_bfe_u32 v74, v23, 16, 1
	v_add3_u32 v23, v23, v74, s7
	global_store_short_d16_hi v[72:73], v23, off offset:2048
	v_mul_f32_e32 v7, 0x3e38aa3b, v7
	v_bfe_u32 v74, v7, 16, 1
	v_add3_u32 v7, v7, v74, s7
	global_store_short_d16_hi v[72:73], v7, off offset:2176
	s_mov_b32 s6, 0x18000
	v_add_co_u32_e32 v72, vcc, s6, v70
	s_nop 1
	v_addc_co_u32_e32 v73, vcc, 0, v71, vcc
	v_mul_f32_e32 v24, 0x3e38aa3b, v24
	v_bfe_u32 v74, v24, 16, 1
	v_add3_u32 v24, v24, v74, s7
	global_store_short_d16_hi v[72:73], v24, off
	v_mul_f32_e32 v8, 0x3e38aa3b, v8
	v_bfe_u32 v74, v8, 16, 1
	v_add3_u32 v8, v8, v74, s7
	global_store_short_d16_hi v[72:73], v8, off offset:128
	v_mul_f32_e32 v25, 0x3e38aa3b, v25
	v_bfe_u32 v74, v25, 16, 1
	v_add3_u32 v25, v25, v74, s7
	global_store_short_d16_hi v[72:73], v25, off offset:2048
	v_mul_f32_e32 v9, 0x3e38aa3b, v9
	v_bfe_u32 v74, v9, 16, 1
	v_add3_u32 v9, v9, v74, s7
	global_store_short_d16_hi v[72:73], v9, off offset:2176
	s_mov_b32 s6, 0x19000
	v_add_co_u32_e32 v72, vcc, s6, v70
	s_nop 1
	v_addc_co_u32_e32 v73, vcc, 0, v71, vcc
	v_mul_f32_e32 v26, 0x3e38aa3b, v26
	v_bfe_u32 v74, v26, 16, 1
	v_add3_u32 v26, v26, v74, s7
	global_store_short_d16_hi v[72:73], v26, off
	v_mul_f32_e32 v10, 0x3e38aa3b, v10
	v_bfe_u32 v74, v10, 16, 1
	v_add3_u32 v10, v10, v74, s7
	global_store_short_d16_hi v[72:73], v10, off offset:128
	v_mul_f32_e32 v27, 0x3e38aa3b, v27
	v_bfe_u32 v74, v27, 16, 1
	v_add3_u32 v27, v27, v74, s7
	global_store_short_d16_hi v[72:73], v27, off offset:2048
	v_mul_f32_e32 v11, 0x3e38aa3b, v11
	v_bfe_u32 v74, v11, 16, 1
	v_add3_u32 v11, v11, v74, s7
	global_store_short_d16_hi v[72:73], v11, off offset:2176
	s_mov_b32 s6, 0x1c000
	v_add_co_u32_e32 v72, vcc, s6, v70
	s_nop 1
	v_addc_co_u32_e32 v73, vcc, 0, v71, vcc
	v_mul_f32_e32 v28, 0x3e38aa3b, v28
	v_bfe_u32 v74, v28, 16, 1
	v_add3_u32 v28, v28, v74, s7
	global_store_short_d16_hi v[72:73], v28, off
	v_mul_f32_e32 v12, 0x3e38aa3b, v12
	v_bfe_u32 v74, v12, 16, 1
	v_add3_u32 v12, v12, v74, s7
	global_store_short_d16_hi v[72:73], v12, off offset:128
	v_mul_f32_e32 v29, 0x3e38aa3b, v29
	v_bfe_u32 v74, v29, 16, 1
	v_add3_u32 v29, v29, v74, s7
	global_store_short_d16_hi v[72:73], v29, off offset:2048
	v_mul_f32_e32 v13, 0x3e38aa3b, v13
	v_bfe_u32 v74, v13, 16, 1
	v_add3_u32 v13, v13, v74, s7
	global_store_short_d16_hi v[72:73], v13, off offset:2176
	s_mov_b32 s6, 0x1d000
	v_add_co_u32_e32 v72, vcc, s6, v70
	s_nop 1
	v_addc_co_u32_e32 v73, vcc, 0, v71, vcc
	v_mul_f32_e32 v30, 0x3e38aa3b, v30
	v_bfe_u32 v74, v30, 16, 1
	v_add3_u32 v30, v30, v74, s7
	global_store_short_d16_hi v[72:73], v30, off
	v_mul_f32_e32 v14, 0x3e38aa3b, v14
	v_bfe_u32 v74, v14, 16, 1
	v_add3_u32 v14, v14, v74, s7
	global_store_short_d16_hi v[72:73], v14, off offset:128
	v_mul_f32_e32 v31, 0x3e38aa3b, v31
	v_bfe_u32 v74, v31, 16, 1
	v_add3_u32 v31, v31, v74, s7
	global_store_short_d16_hi v[72:73], v31, off offset:2048
	v_mul_f32_e32 v15, 0x3e38aa3b, v15
	v_bfe_u32 v74, v15, 16, 1
	v_add3_u32 v15, v15, v74, s7
	global_store_short_d16_hi v[72:73], v15, off offset:2176
	v_readlane_b32 s12, v248, 0
	v_readlane_b32 s13, v248, 1
	v_readlane_b32 s14, v248, 2
	v_readlane_b32 s15, v248, 3
	v_readlane_b32 s16, v248, 4
	v_readlane_b32 s17, v248, 5
	v_readlane_b32 s18, v248, 6
	v_readlane_b32 s19, v248, 7
	s_mov_b64 s[2:3], exec
	s_branch .LBB0_332

.LBB0_2179:
	s_cmp_lt_u32 s2, 8
	s_cbranch_scc0 .Lnqb_slow
	v_lshrrev_b32_e32 v66, 1, v206
	v_and_b32_e32 v66, 0xffffffc0, v66
	v_lshrrev_b32_e32 v67, 3, v206
	v_and_or_b32 v66, v67, 4, v66
	v_lshl_add_u32 v68, s0, 7, v66
	v_lshrrev_b32_e32 v67, 1, v206
	v_and_b32_e32 v67, 32, v67
	v_and_b32_e32 v69, 31, v206
	s_lshl_b32 s4, s2, 7
	v_or3_b32 v66, v69, v67, s4
	v_readlane_b32 s14, v248, 2
	v_readlane_b32 s15, v248, 3
	v_mov_b32_e32 v69, 0
	v_mov_b32_e32 v67, 0
	v_lshlrev_b64 v[70:71], 11, v[68:69]
	v_lshlrev_b32_e32 v66, 1, v66
	v_lshl_add_u64 v[70:71], s[14:15], 0, v[70:71]
	v_lshl_add_u64 v[70:71], v[66:67], 0, v[70:71]
	s_movk_i32 s5, 0x7fff
	v_mul_f32_e32 v50, 0x3e38aa3b, v50
	v_bfe_u32 v74, v50, 16, 1
	v_add3_u32 v50, v50, v74, s5
	global_store_short_d16_hi v[70:71], v50, off
	v_mul_f32_e32 v34, 0x3e38aa3b, v34
	v_bfe_u32 v74, v34, 16, 1
	v_add3_u32 v34, v34, v74, s5
	global_store_short_d16_hi v[70:71], v34, off offset:128
	v_mul_f32_e32 v51, 0x3e38aa3b, v51
	v_bfe_u32 v74, v51, 16, 1
	v_add3_u32 v51, v51, v74, s5
	global_store_short_d16_hi v[70:71], v51, off offset:2048
	v_mul_f32_e32 v35, 0x3e38aa3b, v35
	v_bfe_u32 v74, v35, 16, 1
	v_add3_u32 v35, v35, v74, s5
	global_store_short_d16_hi v[70:71], v35, off offset:2176
	s_mov_b32 s4, 0x1000
	v_add_co_u32_e32 v72, vcc, s4, v70
	s_nop 1
	v_addc_co_u32_e32 v73, vcc, 0, v71, vcc
	v_mul_f32_e32 v52, 0x3e38aa3b, v52
	v_bfe_u32 v74, v52, 16, 1
	v_add3_u32 v52, v52, v74, s5
	global_store_short_d16_hi v[72:73], v52, off
	v_mul_f32_e32 v36, 0x3e38aa3b, v36
	v_bfe_u32 v74, v36, 16, 1
	v_add3_u32 v36, v36, v74, s5
	global_store_short_d16_hi v[72:73], v36, off offset:128
	v_mul_f32_e32 v53, 0x3e38aa3b, v53
	v_bfe_u32 v74, v53, 16, 1
	v_add3_u32 v53, v53, v74, s5
	global_store_short_d16_hi v[72:73], v53, off offset:2048
	v_mul_f32_e32 v37, 0x3e38aa3b, v37
	v_bfe_u32 v74, v37, 16, 1
	v_add3_u32 v37, v37, v74, s5
	global_store_short_d16_hi v[72:73], v37, off offset:2176
	s_mov_b32 s4, 0x4000
	v_add_co_u32_e32 v72, vcc, s4, v70
	s_nop 1
	v_addc_co_u32_e32 v73, vcc, 0, v71, vcc
	v_mul_f32_e32 v54, 0x3e38aa3b, v54
	v_bfe_u32 v74, v54, 16, 1
	v_add3_u32 v54, v54, v74, s5
	global_store_short_d16_hi v[72:73], v54, off
	v_mul_f32_e32 v38, 0x3e38aa3b, v38
	v_bfe_u32 v74, v38, 16, 1
	v_add3_u32 v38, v38, v74, s5
	global_store_short_d16_hi v[72:73], v38, off offset:128
	v_mul_f32_e32 v55, 0x3e38aa3b, v55
	v_bfe_u32 v74, v55, 16, 1
	v_add3_u32 v55, v55, v74, s5
	global_store_short_d16_hi v[72:73], v55, off offset:2048
	v_mul_f32_e32 v39, 0x3e38aa3b, v39
	v_bfe_u32 v74, v39, 16, 1
	v_add3_u32 v39, v39, v74, s5
	global_store_short_d16_hi v[72:73], v39, off offset:2176
	s_mov_b32 s4, 0x5000
	v_add_co_u32_e32 v72, vcc, s4, v70
	s_nop 1
	v_addc_co_u32_e32 v73, vcc, 0, v71, vcc
	v_mul_f32_e32 v56, 0x3e38aa3b, v56
	v_bfe_u32 v74, v56, 16, 1
	v_add3_u32 v56, v56, v74, s5
	global_store_short_d16_hi v[72:73], v56, off
	v_mul_f32_e32 v40, 0x3e38aa3b, v40
	v_bfe_u32 v74, v40, 16, 1
	v_add3_u32 v40, v40, v74, s5
	global_store_short_d16_hi v[72:73], v40, off offset:128
	v_mul_f32_e32 v57, 0x3e38aa3b, v57
	v_bfe_u32 v74, v57, 16, 1
	v_add3_u32 v57, v57, v74, s5
	global_store_short_d16_hi v[72:73], v57, off offset:2048
	v_mul_f32_e32 v41, 0x3e38aa3b, v41
	v_bfe_u32 v74, v41, 16, 1
	v_add3_u32 v41, v41, v74, s5
	global_store_short_d16_hi v[72:73], v41, off offset:2176
	s_mov_b32 s4, 0x8000
	v_add_co_u32_e32 v72, vcc, s4, v70
	s_nop 1
	v_addc_co_u32_e32 v73, vcc, 0, v71, vcc
	v_mul_f32_e32 v58, 0x3e38aa3b, v58
	v_bfe_u32 v74, v58, 16, 1
	v_add3_u32 v58, v58, v74, s5
	global_store_short_d16_hi v[72:73], v58, off
	v_mul_f32_e32 v42, 0x3e38aa3b, v42
	v_bfe_u32 v74, v42, 16, 1
	v_add3_u32 v42, v42, v74, s5
	global_store_short_d16_hi v[72:73], v42, off offset:128
	v_mul_f32_e32 v59, 0x3e38aa3b, v59
	v_bfe_u32 v74, v59, 16, 1
	v_add3_u32 v59, v59, v74, s5
	global_store_short_d16_hi v[72:73], v59, off offset:2048
	v_mul_f32_e32 v43, 0x3e38aa3b, v43
	v_bfe_u32 v74, v43, 16, 1
	v_add3_u32 v43, v43, v74, s5
	global_store_short_d16_hi v[72:73], v43, off offset:2176
	s_mov_b32 s4, 0x9000
	v_add_co_u32_e32 v72, vcc, s4, v70
	s_nop 1
	v_addc_co_u32_e32 v73, vcc, 0, v71, vcc
	v_mul_f32_e32 v60, 0x3e38aa3b, v60
	v_bfe_u32 v74, v60, 16, 1
	v_add3_u32 v60, v60, v74, s5
	global_store_short_d16_hi v[72:73], v60, off
	v_mul_f32_e32 v44, 0x3e38aa3b, v44
	v_bfe_u32 v74, v44, 16, 1
	v_add3_u32 v44, v44, v74, s5
	global_store_short_d16_hi v[72:73], v44, off offset:128
	v_mul_f32_e32 v61, 0x3e38aa3b, v61
	v_bfe_u32 v74, v61, 16, 1
	v_add3_u32 v61, v61, v74, s5
	global_store_short_d16_hi v[72:73], v61, off offset:2048
	v_mul_f32_e32 v45, 0x3e38aa3b, v45
	v_bfe_u32 v74, v45, 16, 1
	v_add3_u32 v45, v45, v74, s5
	global_store_short_d16_hi v[72:73], v45, off offset:2176
	s_mov_b32 s4, 0xc000
	v_add_co_u32_e32 v72, vcc, s4, v70
	s_nop 1
	v_addc_co_u32_e32 v73, vcc, 0, v71, vcc
	v_mul_f32_e32 v62, 0x3e38aa3b, v62
	v_bfe_u32 v74, v62, 16, 1
	v_add3_u32 v62, v62, v74, s5
	global_store_short_d16_hi v[72:73], v62, off
	v_mul_f32_e32 v46, 0x3e38aa3b, v46
	v_bfe_u32 v74, v46, 16, 1
	v_add3_u32 v46, v46, v74, s5
	global_store_short_d16_hi v[72:73], v46, off offset:128
	v_mul_f32_e32 v63, 0x3e38aa3b, v63
	v_bfe_u32 v74, v63, 16, 1
	v_add3_u32 v63, v63, v74, s5
	global_store_short_d16_hi v[72:73], v63, off offset:2048
	v_mul_f32_e32 v47, 0x3e38aa3b, v47
	v_bfe_u32 v74, v47, 16, 1
	v_add3_u32 v47, v47, v74, s5
	global_store_short_d16_hi v[72:73], v47, off offset:2176
	s_mov_b32 s4, 0xd000
	v_add_co_u32_e32 v72, vcc, s4, v70
	s_nop 1
	v_addc_co_u32_e32 v73, vcc, 0, v71, vcc
	v_mul_f32_e32 v64, 0x3e38aa3b, v64
	v_bfe_u32 v74, v64, 16, 1
	v_add3_u32 v64, v64, v74, s5
	global_store_short_d16_hi v[72:73], v64, off
	v_mul_f32_e32 v48, 0x3e38aa3b, v48
	v_bfe_u32 v74, v48, 16, 1
	v_add3_u32 v48, v48, v74, s5
	global_store_short_d16_hi v[72:73], v48, off offset:128
	v_mul_f32_e32 v65, 0x3e38aa3b, v65
	v_bfe_u32 v74, v65, 16, 1
	v_add3_u32 v65, v65, v74, s5
	global_store_short_d16_hi v[72:73], v65, off offset:2048
	v_mul_f32_e32 v49, 0x3e38aa3b, v49
	v_bfe_u32 v74, v49, 16, 1
	v_add3_u32 v49, v49, v74, s5
	global_store_short_d16_hi v[72:73], v49, off offset:2176
	s_mov_b32 s4, 0x10000
	v_add_co_u32_e32 v72, vcc, s4, v70
	s_nop 1
	v_addc_co_u32_e32 v73, vcc, 0, v71, vcc
	v_mul_f32_e32 v16, 0x3e38aa3b, v16
	v_bfe_u32 v74, v16, 16, 1
	v_add3_u32 v16, v16, v74, s5
	global_store_short_d16_hi v[72:73], v16, off
	v_mul_f32_e32 v0, 0x3e38aa3b, v0
	v_bfe_u32 v74, v0, 16, 1
	v_add3_u32 v0, v0, v74, s5
	global_store_short_d16_hi v[72:73], v0, off offset:128
	v_mul_f32_e32 v17, 0x3e38aa3b, v17
	v_bfe_u32 v74, v17, 16, 1
	v_add3_u32 v17, v17, v74, s5
	global_store_short_d16_hi v[72:73], v17, off offset:2048
	v_mul_f32_e32 v1, 0x3e38aa3b, v1
	v_bfe_u32 v74, v1, 16, 1
	v_add3_u32 v1, v1, v74, s5
	global_store_short_d16_hi v[72:73], v1, off offset:2176
	s_mov_b32 s4, 0x11000
	v_add_co_u32_e32 v72, vcc, s4, v70
	s_nop 1
	v_addc_co_u32_e32 v73, vcc, 0, v71, vcc
	v_mul_f32_e32 v18, 0x3e38aa3b, v18
	v_bfe_u32 v74, v18, 16, 1
	v_add3_u32 v18, v18, v74, s5
	global_store_short_d16_hi v[72:73], v18, off
	v_mul_f32_e32 v2, 0x3e38aa3b, v2
	v_bfe_u32 v74, v2, 16, 1
	v_add3_u32 v2, v2, v74, s5
	global_store_short_d16_hi v[72:73], v2, off offset:128
	v_mul_f32_e32 v19, 0x3e38aa3b, v19
	v_bfe_u32 v74, v19, 16, 1
	v_add3_u32 v19, v19, v74, s5
	global_store_short_d16_hi v[72:73], v19, off offset:2048
	v_mul_f32_e32 v3, 0x3e38aa3b, v3
	v_bfe_u32 v74, v3, 16, 1
	v_add3_u32 v3, v3, v74, s5
	global_store_short_d16_hi v[72:73], v3, off offset:2176
	s_mov_b32 s4, 0x14000
	v_add_co_u32_e32 v72, vcc, s4, v70
	s_nop 1
	v_addc_co_u32_e32 v73, vcc, 0, v71, vcc
	v_mul_f32_e32 v20, 0x3e38aa3b, v20
	v_bfe_u32 v74, v20, 16, 1
	v_add3_u32 v20, v20, v74, s5
	global_store_short_d16_hi v[72:73], v20, off
	v_mul_f32_e32 v4, 0x3e38aa3b, v4
	v_bfe_u32 v74, v4, 16, 1
	v_add3_u32 v4, v4, v74, s5
	global_store_short_d16_hi v[72:73], v4, off offset:128
	v_mul_f32_e32 v21, 0x3e38aa3b, v21
	v_bfe_u32 v74, v21, 16, 1
	v_add3_u32 v21, v21, v74, s5
	global_store_short_d16_hi v[72:73], v21, off offset:2048
	v_mul_f32_e32 v5, 0x3e38aa3b, v5
	v_bfe_u32 v74, v5, 16, 1
	v_add3_u32 v5, v5, v74, s5
	global_store_short_d16_hi v[72:73], v5, off offset:2176
	s_mov_b32 s4, 0x15000
	v_add_co_u32_e32 v72, vcc, s4, v70
	s_nop 1
	v_addc_co_u32_e32 v73, vcc, 0, v71, vcc
	v_mul_f32_e32 v22, 0x3e38aa3b, v22
	v_bfe_u32 v74, v22, 16, 1
	v_add3_u32 v22, v22, v74, s5
	global_store_short_d16_hi v[72:73], v22, off
	v_mul_f32_e32 v6, 0x3e38aa3b, v6
	v_bfe_u32 v74, v6, 16, 1
	v_add3_u32 v6, v6, v74, s5
	global_store_short_d16_hi v[72:73], v6, off offset:128
	v_mul_f32_e32 v23, 0x3e38aa3b, v23
	v_bfe_u32 v74, v23, 16, 1
	v_add3_u32 v23, v23, v74, s5
	global_store_short_d16_hi v[72:73], v23, off offset:2048
	v_mul_f32_e32 v7, 0x3e38aa3b, v7
	v_bfe_u32 v74, v7, 16, 1
	v_add3_u32 v7, v7, v74, s5
	global_store_short_d16_hi v[72:73], v7, off offset:2176
	s_mov_b32 s4, 0x18000
	v_add_co_u32_e32 v72, vcc, s4, v70
	s_nop 1
	v_addc_co_u32_e32 v73, vcc, 0, v71, vcc
	v_mul_f32_e32 v24, 0x3e38aa3b, v24
	v_bfe_u32 v74, v24, 16, 1
	v_add3_u32 v24, v24, v74, s5
	global_store_short_d16_hi v[72:73], v24, off
	v_mul_f32_e32 v8, 0x3e38aa3b, v8
	v_bfe_u32 v74, v8, 16, 1
	v_add3_u32 v8, v8, v74, s5
	global_store_short_d16_hi v[72:73], v8, off offset:128
	v_mul_f32_e32 v25, 0x3e38aa3b, v25
	v_bfe_u32 v74, v25, 16, 1
	v_add3_u32 v25, v25, v74, s5
	global_store_short_d16_hi v[72:73], v25, off offset:2048
	v_mul_f32_e32 v9, 0x3e38aa3b, v9
	v_bfe_u32 v74, v9, 16, 1
	v_add3_u32 v9, v9, v74, s5
	global_store_short_d16_hi v[72:73], v9, off offset:2176
	s_mov_b32 s4, 0x19000
	v_add_co_u32_e32 v72, vcc, s4, v70
	s_nop 1
	v_addc_co_u32_e32 v73, vcc, 0, v71, vcc
	v_mul_f32_e32 v26, 0x3e38aa3b, v26
	v_bfe_u32 v74, v26, 16, 1
	v_add3_u32 v26, v26, v74, s5
	global_store_short_d16_hi v[72:73], v26, off
	v_mul_f32_e32 v10, 0x3e38aa3b, v10
	v_bfe_u32 v74, v10, 16, 1
	v_add3_u32 v10, v10, v74, s5
	global_store_short_d16_hi v[72:73], v10, off offset:128
	v_mul_f32_e32 v27, 0x3e38aa3b, v27
	v_bfe_u32 v74, v27, 16, 1
	v_add3_u32 v27, v27, v74, s5
	global_store_short_d16_hi v[72:73], v27, off offset:2048
	v_mul_f32_e32 v11, 0x3e38aa3b, v11
	v_bfe_u32 v74, v11, 16, 1
	v_add3_u32 v11, v11, v74, s5
	global_store_short_d16_hi v[72:73], v11, off offset:2176
	s_mov_b32 s4, 0x1c000
	v_add_co_u32_e32 v72, vcc, s4, v70
	s_nop 1
	v_addc_co_u32_e32 v73, vcc, 0, v71, vcc
	v_mul_f32_e32 v28, 0x3e38aa3b, v28
	v_bfe_u32 v74, v28, 16, 1
	v_add3_u32 v28, v28, v74, s5
	global_store_short_d16_hi v[72:73], v28, off
	v_mul_f32_e32 v12, 0x3e38aa3b, v12
	v_bfe_u32 v74, v12, 16, 1
	v_add3_u32 v12, v12, v74, s5
	global_store_short_d16_hi v[72:73], v12, off offset:128
	v_mul_f32_e32 v29, 0x3e38aa3b, v29
	v_bfe_u32 v74, v29, 16, 1
	v_add3_u32 v29, v29, v74, s5
	global_store_short_d16_hi v[72:73], v29, off offset:2048
	v_mul_f32_e32 v13, 0x3e38aa3b, v13
	v_bfe_u32 v74, v13, 16, 1
	v_add3_u32 v13, v13, v74, s5
	global_store_short_d16_hi v[72:73], v13, off offset:2176
	s_mov_b32 s4, 0x1d000
	v_add_co_u32_e32 v72, vcc, s4, v70
	s_nop 1
	v_addc_co_u32_e32 v73, vcc, 0, v71, vcc
	v_mul_f32_e32 v30, 0x3e38aa3b, v30
	v_bfe_u32 v74, v30, 16, 1
	v_add3_u32 v30, v30, v74, s5
	global_store_short_d16_hi v[72:73], v30, off
	v_mul_f32_e32 v14, 0x3e38aa3b, v14
	v_bfe_u32 v74, v14, 16, 1
	v_add3_u32 v14, v14, v74, s5
	global_store_short_d16_hi v[72:73], v14, off offset:128
	v_mul_f32_e32 v31, 0x3e38aa3b, v31
	v_bfe_u32 v74, v31, 16, 1
	v_add3_u32 v31, v31, v74, s5
	global_store_short_d16_hi v[72:73], v31, off offset:2048
	v_mul_f32_e32 v15, 0x3e38aa3b, v15
	v_bfe_u32 v74, v15, 16, 1
	v_add3_u32 v15, v15, v74, s5
	global_store_short_d16_hi v[72:73], v15, off offset:2176
	v_readlane_b32 s12, v248, 0
	v_readlane_b32 s13, v248, 1
	v_readlane_b32 s14, v248, 2
	v_readlane_b32 s15, v248, 3
	v_readlane_b32 s16, v248, 4
	v_readlane_b32 s17, v248, 5
	v_readlane_b32 s18, v248, 6
	v_readlane_b32 s19, v248, 7
	v_readlane_b32 s20, v249, 14
	v_readlane_b32 s21, v249, 15
	s_mov_b64 s[0:1], exec
	s_branch .LBB0_2167
